# inter-chunk scan: state stores plain (the barrier's release, hidden under the attention tile that follows, writes them back) instead of write-through
# speedup vs baseline: 1.0033x; 1.0033x over previous
; __device__ __forceinline__ float bf2f(bf16 v) { return __uint_as_float(((unsigned)v) << 16); }
; __device__ __forceinline__ unsigned f2bfu(float f) { return (unsigned)__builtin_bit_cast(unsigned short, (__bf16)f); }
; __global__ void __launch_bounds__(NTHR, 2) k_main(Args a) {
;     ...
;         for (int idx = gtid; idx < 2 * 8 * 8192; idx += gthreads) {
;             const int pn = idx & 8191, h = (idx >> 13) & 7, b = idx >> 16;
;             float run = 0.f;
; #pragma unroll 1
;             for (int c0 = 0; c0 < 64; c0 += 8) {
;                 float st[8], dc[8];
; #pragma unroll
;                 for (int j = 0; j < 8; ++j) { const int bch = (b * 64 + c0 + j) * 8 + h; st[j] = bf2f(__builtin_nontemporal_load(&STATES[(size_t)bch * 8192 + pn])); dc[j] = CDEC[bch]; }
; #pragma unroll
;                 for (int j = 0; j < 8; ++j) { const int bch = (b * 64 + c0 + j) * 8 + h; __builtin_amdgcn_raw_buffer_store_b16((short)f2bfu(run), rsPV, (int)(((unsigned)bch * 8192u + (unsigned)pn) * 2u), 0, 16); run = dc[j] * run + st[j]; }
;             }
;         }
.LBB0_377:
	v_and_b32_e32 v2, 0x1fff, v8
	v_ashrrev_i32_e32 v10, 10, v8
	v_lshlrev_b32_e32 v2, 1, v2
	v_lshl_add_u64 v[4:5], s[58:59], 0, v[2:3]
	v_lshrrev_b32_e32 v2, 6, v10
	v_bfe_u32 v6, v8, 13, 3
	v_and_b32_e32 v7, 0x1fffe, v9
	v_lshlrev_b32_e32 v10, 9, v2
	v_lshlrev_b32_e32 v2, 23, v2
	v_or3_b32 v6, v10, v6, 56
	v_or3_b32 v2, v2, v7, s10
	s_mov_b32 s12, -8
	v_mov_b32_e32 v10, 0
	v_subrev_u32_e32 v46, 56, v6
	v_and_b32_e32 v47, 0x1fff, v8
	v_lshlrev_b32_e32 v47, 1, v47
	v_lshl_add_u32 v47, v46, 14, v47
	v_lshlrev_b32_e32 v50, 2, v46
	v_add_u32_e32 v51, 0xfff20000, v2
	v_readfirstlane_b32 s44, v50
	s_nop 3
	s_add_u32 s46, s82, s44
	s_addc_u32 s47, s83, 0
	global_load_ushort v128, v47, s[58:59] nt
	v_add_u32_e32 v53, 0x20000, v47
	global_load_ushort v129, v53, s[58:59] nt
	v_add_u32_e32 v53, 0x40000, v47
	global_load_ushort v130, v53, s[58:59] nt
	v_add_u32_e32 v53, 0x60000, v47
	global_load_ushort v131, v53, s[58:59] nt
	v_add_u32_e32 v53, 0x80000, v47
	global_load_ushort v132, v53, s[58:59] nt
	v_add_u32_e32 v53, 0xa0000, v47
	global_load_ushort v133, v53, s[58:59] nt
	v_add_u32_e32 v53, 0xc0000, v47
	global_load_ushort v134, v53, s[58:59] nt
	v_add_u32_e32 v53, 0xe0000, v47
	global_load_ushort v135, v53, s[58:59] nt
	v_add_u32_e32 v53, 0x100000, v47
	global_load_ushort v136, v53, s[58:59] nt
	v_add_u32_e32 v53, 0x120000, v47
	global_load_ushort v137, v53, s[58:59] nt
	v_add_u32_e32 v53, 0x140000, v47
	global_load_ushort v138, v53, s[58:59] nt
	v_add_u32_e32 v53, 0x160000, v47
	global_load_ushort v139, v53, s[58:59] nt
	v_add_u32_e32 v53, 0x180000, v47
	global_load_ushort v140, v53, s[58:59] nt
	v_add_u32_e32 v53, 0x1a0000, v47
	global_load_ushort v141, v53, s[58:59] nt
	v_add_u32_e32 v53, 0x1c0000, v47
	global_load_ushort v142, v53, s[58:59] nt
	v_add_u32_e32 v53, 0x1e0000, v47
	global_load_ushort v143, v53, s[58:59] nt
	s_load_dword s64, s[46:47], 0x0
	s_load_dword s65, s[46:47], 0x20
	s_load_dword s66, s[46:47], 0x40
	s_load_dword s67, s[46:47], 0x60
	s_load_dword s68, s[46:47], 0x80
	s_load_dword s69, s[46:47], 0xa0
	s_load_dword s70, s[46:47], 0xc0
	s_load_dword s71, s[46:47], 0xe0
	s_load_dword s72, s[46:47], 0x100
	s_load_dword s73, s[46:47], 0x120
	s_load_dword s74, s[46:47], 0x140
	s_load_dword s75, s[46:47], 0x160
	s_load_dword s76, s[46:47], 0x180
	s_load_dword s77, s[46:47], 0x1a0
	s_load_dword s78, s[46:47], 0x1c0
	s_load_dword s79, s[46:47], 0x1e0
	v_add_u32_e32 v53, 0x200000, v47
	global_load_ushort v144, v53, s[58:59] nt
	v_add_u32_e32 v53, 0x220000, v47
	global_load_ushort v145, v53, s[58:59] nt
	v_add_u32_e32 v53, 0x240000, v47
	global_load_ushort v146, v53, s[58:59] nt
	v_add_u32_e32 v53, 0x260000, v47
	global_load_ushort v147, v53, s[58:59] nt
	v_add_u32_e32 v53, 0x280000, v47
	global_load_ushort v148, v53, s[58:59] nt
	v_add_u32_e32 v53, 0x2a0000, v47
	global_load_ushort v149, v53, s[58:59] nt
	v_add_u32_e32 v53, 0x2c0000, v47
	global_load_ushort v150, v53, s[58:59] nt
	v_add_u32_e32 v53, 0x2e0000, v47
	global_load_ushort v151, v53, s[58:59] nt
	v_add_u32_e32 v53, 0x300000, v47
	global_load_ushort v152, v53, s[58:59] nt
	v_add_u32_e32 v53, 0x320000, v47
	global_load_ushort v153, v53, s[58:59] nt
	v_add_u32_e32 v53, 0x340000, v47
	global_load_ushort v154, v53, s[58:59] nt
	v_add_u32_e32 v53, 0x360000, v47
	global_load_ushort v155, v53, s[58:59] nt
	v_add_u32_e32 v53, 0x380000, v47
	global_load_ushort v156, v53, s[58:59] nt
	v_add_u32_e32 v53, 0x3a0000, v47
	global_load_ushort v157, v53, s[58:59] nt
	v_add_u32_e32 v53, 0x3c0000, v47
	global_load_ushort v158, v53, s[58:59] nt
	v_add_u32_e32 v53, 0x3e0000, v47
	global_load_ushort v159, v53, s[58:59] nt
	s_waitcnt lgkmcnt(0)
	s_load_dword s21, s[46:47], 0x200
	s_load_dword s22, s[46:47], 0x220
	s_load_dword s23, s[46:47], 0x240
	s_load_dword s24, s[46:47], 0x260
	s_load_dword s25, s[46:47], 0x280
	s_load_dword s26, s[46:47], 0x2a0
	s_load_dword s27, s[46:47], 0x2c0
	s_load_dword s37, s[46:47], 0x2e0
	s_load_dword s38, s[46:47], 0x300
	s_load_dword s39, s[46:47], 0x320
	s_load_dword s40, s[46:47], 0x340
	s_load_dword s41, s[46:47], 0x360
	s_load_dword s45, s[46:47], 0x380
	s_load_dword s48, s[46:47], 0x3a0
	s_load_dword s49, s[46:47], 0x3c0
	s_load_dword s32, s[46:47], 0x3e0
	v_cvt_pk_bf16_f32 v52, v10, v10
	buffer_store_short v52, v51, s[4:7], 0 offen
	s_waitcnt vmcnt(32)
	v_lshlrev_b32_e32 v128, 16, v128
	v_fmac_f32_e32 v128, s64, v10
	v_mov_b32_e32 v10, v128
	v_cvt_pk_bf16_f32 v52, v10, v10
	s_mov_b32 s13, 0x20000
	buffer_store_short v52, v51, s[4:7], s13 offen
	s_waitcnt vmcnt(32)
	v_lshlrev_b32_e32 v129, 16, v129
	v_fmac_f32_e32 v129, s65, v10
	v_mov_b32_e32 v10, v129
	v_cvt_pk_bf16_f32 v52, v10, v10
	s_mov_b32 s13, 0x40000
	buffer_store_short v52, v51, s[4:7], s13 offen
	s_waitcnt vmcnt(32)
	v_lshlrev_b32_e32 v130, 16, v130
	v_fmac_f32_e32 v130, s66, v10
	v_mov_b32_e32 v10, v130
	v_cvt_pk_bf16_f32 v52, v10, v10
	s_mov_b32 s13, 0x60000
	buffer_store_short v52, v51, s[4:7], s13 offen
	s_waitcnt vmcnt(32)
	v_lshlrev_b32_e32 v131, 16, v131
	v_fmac_f32_e32 v131, s67, v10
	v_mov_b32_e32 v10, v131
	v_cvt_pk_bf16_f32 v52, v10, v10
	s_mov_b32 s13, 0x80000
	buffer_store_short v52, v51, s[4:7], s13 offen
	s_waitcnt vmcnt(32)
	v_lshlrev_b32_e32 v132, 16, v132
	v_fmac_f32_e32 v132, s68, v10
	v_mov_b32_e32 v10, v132
	v_cvt_pk_bf16_f32 v52, v10, v10
	s_mov_b32 s13, 0xa0000
	buffer_store_short v52, v51, s[4:7], s13 offen
	s_waitcnt vmcnt(32)
	v_lshlrev_b32_e32 v133, 16, v133
	v_fmac_f32_e32 v133, s69, v10
	v_mov_b32_e32 v10, v133
	v_cvt_pk_bf16_f32 v52, v10, v10
	s_mov_b32 s13, 0xc0000
	buffer_store_short v52, v51, s[4:7], s13 offen
	s_waitcnt vmcnt(32)
; __device__ __forceinline__ float bf2f(bf16 v) { return __uint_as_float(((unsigned)v) << 16); }
; __device__ __forceinline__ unsigned f2bfu(float f) { return (unsigned)__builtin_bit_cast(unsigned short, (__bf16)f); }
; __global__ void __launch_bounds__(NTHR, 2) k_main(Args a) {
;     ...
;         for (int idx = gtid; idx < 2 * 8 * 8192; idx += gthreads) {
;             const int pn = idx & 8191, h = (idx >> 13) & 7, b = idx >> 16;
;             float run = 0.f;
; #pragma unroll 1
;             for (int c0 = 0; c0 < 64; c0 += 8) {
;                 float st[8], dc[8];
; #pragma unroll
;                 for (int j = 0; j < 8; ++j) { const int bch = (b * 64 + c0 + j) * 8 + h; st[j] = bf2f(__builtin_nontemporal_load(&STATES[(size_t)bch * 8192 + pn])); dc[j] = CDEC[bch]; }
; #pragma unroll
;                 for (int j = 0; j < 8; ++j) { const int bch = (b * 64 + c0 + j) * 8 + h; __builtin_amdgcn_raw_buffer_store_b16((short)f2bfu(run), rsPV, (int)(((unsigned)bch * 8192u + (unsigned)pn) * 2u), 0, 16); run = dc[j] * run + st[j]; }
;             }
;         }
	v_lshlrev_b32_e32 v134, 16, v134
	v_fmac_f32_e32 v134, s70, v10
	v_mov_b32_e32 v10, v134
	v_cvt_pk_bf16_f32 v52, v10, v10
	s_mov_b32 s13, 0xe0000
	buffer_store_short v52, v51, s[4:7], s13 offen
	s_waitcnt vmcnt(32)
	v_lshlrev_b32_e32 v135, 16, v135
	v_fmac_f32_e32 v135, s71, v10
	v_mov_b32_e32 v10, v135
	v_cvt_pk_bf16_f32 v52, v10, v10
	s_mov_b32 s13, 0x100000
	buffer_store_short v52, v51, s[4:7], s13 offen
	s_waitcnt vmcnt(32)
	v_lshlrev_b32_e32 v136, 16, v136
	v_fmac_f32_e32 v136, s72, v10
	v_mov_b32_e32 v10, v136
	v_cvt_pk_bf16_f32 v52, v10, v10
	s_mov_b32 s13, 0x120000
	buffer_store_short v52, v51, s[4:7], s13 offen
	s_waitcnt vmcnt(32)
	v_lshlrev_b32_e32 v137, 16, v137
	v_fmac_f32_e32 v137, s73, v10
	v_mov_b32_e32 v10, v137
	v_cvt_pk_bf16_f32 v52, v10, v10
	s_mov_b32 s13, 0x140000
	buffer_store_short v52, v51, s[4:7], s13 offen
	s_waitcnt vmcnt(32)
	v_lshlrev_b32_e32 v138, 16, v138
	v_fmac_f32_e32 v138, s74, v10
	v_mov_b32_e32 v10, v138
	v_cvt_pk_bf16_f32 v52, v10, v10
	s_mov_b32 s13, 0x160000
	buffer_store_short v52, v51, s[4:7], s13 offen
	s_waitcnt vmcnt(32)
	v_lshlrev_b32_e32 v139, 16, v139
	v_fmac_f32_e32 v139, s75, v10
	v_mov_b32_e32 v10, v139
	v_cvt_pk_bf16_f32 v52, v10, v10
	s_mov_b32 s13, 0x180000
	buffer_store_short v52, v51, s[4:7], s13 offen
	s_waitcnt vmcnt(32)
	v_lshlrev_b32_e32 v140, 16, v140
	v_fmac_f32_e32 v140, s76, v10
	v_mov_b32_e32 v10, v140
	v_cvt_pk_bf16_f32 v52, v10, v10
	s_mov_b32 s13, 0x1a0000
	buffer_store_short v52, v51, s[4:7], s13 offen
	s_waitcnt vmcnt(32)
	v_lshlrev_b32_e32 v141, 16, v141
	v_fmac_f32_e32 v141, s77, v10
	v_mov_b32_e32 v10, v141
	v_cvt_pk_bf16_f32 v52, v10, v10
	s_mov_b32 s13, 0x1c0000
	buffer_store_short v52, v51, s[4:7], s13 offen
	s_waitcnt vmcnt(32)
	v_lshlrev_b32_e32 v142, 16, v142
	v_fmac_f32_e32 v142, s78, v10
	v_mov_b32_e32 v10, v142
	v_cvt_pk_bf16_f32 v52, v10, v10
	s_mov_b32 s13, 0x1e0000
	buffer_store_short v52, v51, s[4:7], s13 offen
	s_waitcnt vmcnt(32)
	v_lshlrev_b32_e32 v143, 16, v143
	v_fmac_f32_e32 v143, s79, v10
	v_mov_b32_e32 v10, v143
	v_add_u32_e32 v53, 0x400000, v47
	global_load_ushort v128, v53, s[58:59] nt
	v_add_u32_e32 v53, 0x420000, v47
	global_load_ushort v129, v53, s[58:59] nt
	v_add_u32_e32 v53, 0x440000, v47
	global_load_ushort v130, v53, s[58:59] nt
	v_add_u32_e32 v53, 0x460000, v47
	global_load_ushort v131, v53, s[58:59] nt
	v_add_u32_e32 v53, 0x480000, v47
	global_load_ushort v132, v53, s[58:59] nt
	v_add_u32_e32 v53, 0x4a0000, v47
	global_load_ushort v133, v53, s[58:59] nt
	v_add_u32_e32 v53, 0x4c0000, v47
	global_load_ushort v134, v53, s[58:59] nt
	v_add_u32_e32 v53, 0x4e0000, v47
	global_load_ushort v135, v53, s[58:59] nt
	v_add_u32_e32 v53, 0x500000, v47
	global_load_ushort v136, v53, s[58:59] nt
	v_add_u32_e32 v53, 0x520000, v47
	global_load_ushort v137, v53, s[58:59] nt
	v_add_u32_e32 v53, 0x540000, v47
	global_load_ushort v138, v53, s[58:59] nt
	v_add_u32_e32 v53, 0x560000, v47
	global_load_ushort v139, v53, s[58:59] nt
	v_add_u32_e32 v53, 0x580000, v47
	global_load_ushort v140, v53, s[58:59] nt
	v_add_u32_e32 v53, 0x5a0000, v47
	global_load_ushort v141, v53, s[58:59] nt
	v_add_u32_e32 v53, 0x5c0000, v47
	global_load_ushort v142, v53, s[58:59] nt
	v_add_u32_e32 v53, 0x5e0000, v47
	global_load_ushort v143, v53, s[58:59] nt
	s_waitcnt lgkmcnt(0)
	s_load_dword s64, s[46:47], 0x400
	s_load_dword s65, s[46:47], 0x420
	s_load_dword s66, s[46:47], 0x440
	s_load_dword s67, s[46:47], 0x460
	s_load_dword s68, s[46:47], 0x480
	s_load_dword s69, s[46:47], 0x4a0
	s_load_dword s70, s[46:47], 0x4c0
	s_load_dword s71, s[46:47], 0x4e0
	s_load_dword s72, s[46:47], 0x500
	s_load_dword s73, s[46:47], 0x520
	s_load_dword s74, s[46:47], 0x540
	s_load_dword s75, s[46:47], 0x560
	s_load_dword s76, s[46:47], 0x580
	s_load_dword s77, s[46:47], 0x5a0
	s_load_dword s78, s[46:47], 0x5c0
	s_load_dword s79, s[46:47], 0x5e0
	v_cvt_pk_bf16_f32 v52, v10, v10
	s_mov_b32 s13, 0x200000
	buffer_store_short v52, v51, s[4:7], s13 offen
	s_waitcnt vmcnt(48)
	v_lshlrev_b32_e32 v144, 16, v144
	v_fmac_f32_e32 v144, s21, v10
	v_mov_b32_e32 v10, v144
	v_cvt_pk_bf16_f32 v52, v10, v10
	s_mov_b32 s13, 0x220000
	buffer_store_short v52, v51, s[4:7], s13 offen
	s_waitcnt vmcnt(48)
	v_lshlrev_b32_e32 v145, 16, v145
	v_fmac_f32_e32 v145, s22, v10
	v_mov_b32_e32 v10, v145
	v_cvt_pk_bf16_f32 v52, v10, v10
	s_mov_b32 s13, 0x240000
	buffer_store_short v52, v51, s[4:7], s13 offen
	s_waitcnt vmcnt(48)
	v_lshlrev_b32_e32 v146, 16, v146
	v_fmac_f32_e32 v146, s23, v10
	v_mov_b32_e32 v10, v146
	v_cvt_pk_bf16_f32 v52, v10, v10
	s_mov_b32 s13, 0x260000
	buffer_store_short v52, v51, s[4:7], s13 offen
	s_waitcnt vmcnt(48)
	v_lshlrev_b32_e32 v147, 16, v147
	v_fmac_f32_e32 v147, s24, v10
	v_mov_b32_e32 v10, v147
	v_cvt_pk_bf16_f32 v52, v10, v10
	s_mov_b32 s13, 0x280000
	buffer_store_short v52, v51, s[4:7], s13 offen
	s_waitcnt vmcnt(48)
	v_lshlrev_b32_e32 v148, 16, v148
	v_fmac_f32_e32 v148, s25, v10
	v_mov_b32_e32 v10, v148
	v_cvt_pk_bf16_f32 v52, v10, v10
	s_mov_b32 s13, 0x2a0000
	buffer_store_short v52, v51, s[4:7], s13 offen
	s_waitcnt vmcnt(48)
	v_lshlrev_b32_e32 v149, 16, v149
	v_fmac_f32_e32 v149, s26, v10
	v_mov_b32_e32 v10, v149
	v_cvt_pk_bf16_f32 v52, v10, v10
	s_mov_b32 s13, 0x2c0000
	buffer_store_short v52, v51, s[4:7], s13 offen
	s_waitcnt vmcnt(48)
	v_lshlrev_b32_e32 v150, 16, v150
	v_fmac_f32_e32 v150, s27, v10
	v_mov_b32_e32 v10, v150
	v_cvt_pk_bf16_f32 v52, v10, v10
	s_mov_b32 s13, 0x2e0000
	buffer_store_short v52, v51, s[4:7], s13 offen
	s_waitcnt vmcnt(48)
	v_lshlrev_b32_e32 v151, 16, v151
	v_fmac_f32_e32 v151, s37, v10
	v_mov_b32_e32 v10, v151
	v_cvt_pk_bf16_f32 v52, v10, v10
	s_mov_b32 s13, 0x300000
	buffer_store_short v52, v51, s[4:7], s13 offen
	s_waitcnt vmcnt(48)
; __device__ __forceinline__ float bf2f(bf16 v) { return __uint_as_float(((unsigned)v) << 16); }
; __device__ __forceinline__ unsigned f2bfu(float f) { return (unsigned)__builtin_bit_cast(unsigned short, (__bf16)f); }
; __global__ void __launch_bounds__(NTHR, 2) k_main(Args a) {
;     ...
;         for (int idx = gtid; idx < 2 * 8 * 8192; idx += gthreads) {
;             const int pn = idx & 8191, h = (idx >> 13) & 7, b = idx >> 16;
;             float run = 0.f;
; #pragma unroll 1
;             for (int c0 = 0; c0 < 64; c0 += 8) {
;                 float st[8], dc[8];
; #pragma unroll
;                 for (int j = 0; j < 8; ++j) { const int bch = (b * 64 + c0 + j) * 8 + h; st[j] = bf2f(__builtin_nontemporal_load(&STATES[(size_t)bch * 8192 + pn])); dc[j] = CDEC[bch]; }
; #pragma unroll
;                 for (int j = 0; j < 8; ++j) { const int bch = (b * 64 + c0 + j) * 8 + h; __builtin_amdgcn_raw_buffer_store_b16((short)f2bfu(run), rsPV, (int)(((unsigned)bch * 8192u + (unsigned)pn) * 2u), 0, 16); run = dc[j] * run + st[j]; }
;             }
;         }
	v_lshlrev_b32_e32 v152, 16, v152
	v_fmac_f32_e32 v152, s38, v10
	v_mov_b32_e32 v10, v152
	v_cvt_pk_bf16_f32 v52, v10, v10
	s_mov_b32 s13, 0x320000
	buffer_store_short v52, v51, s[4:7], s13 offen
	s_waitcnt vmcnt(48)
	v_lshlrev_b32_e32 v153, 16, v153
	v_fmac_f32_e32 v153, s39, v10
	v_mov_b32_e32 v10, v153
	v_cvt_pk_bf16_f32 v52, v10, v10
	s_mov_b32 s13, 0x340000
	buffer_store_short v52, v51, s[4:7], s13 offen
	s_waitcnt vmcnt(48)
	v_lshlrev_b32_e32 v154, 16, v154
	v_fmac_f32_e32 v154, s40, v10
	v_mov_b32_e32 v10, v154
	v_cvt_pk_bf16_f32 v52, v10, v10
	s_mov_b32 s13, 0x360000
	buffer_store_short v52, v51, s[4:7], s13 offen
	s_waitcnt vmcnt(48)
	v_lshlrev_b32_e32 v155, 16, v155
	v_fmac_f32_e32 v155, s41, v10
	v_mov_b32_e32 v10, v155
	v_cvt_pk_bf16_f32 v52, v10, v10
	s_mov_b32 s13, 0x380000
	buffer_store_short v52, v51, s[4:7], s13 offen
	s_waitcnt vmcnt(48)
	v_lshlrev_b32_e32 v156, 16, v156
	v_fmac_f32_e32 v156, s45, v10
	v_mov_b32_e32 v10, v156
	v_cvt_pk_bf16_f32 v52, v10, v10
	s_mov_b32 s13, 0x3a0000
	buffer_store_short v52, v51, s[4:7], s13 offen
	s_waitcnt vmcnt(48)
	v_lshlrev_b32_e32 v157, 16, v157
	v_fmac_f32_e32 v157, s48, v10
	v_mov_b32_e32 v10, v157
	v_cvt_pk_bf16_f32 v52, v10, v10
	s_mov_b32 s13, 0x3c0000
	buffer_store_short v52, v51, s[4:7], s13 offen
	s_waitcnt vmcnt(48)
	v_lshlrev_b32_e32 v158, 16, v158
	v_fmac_f32_e32 v158, s49, v10
	v_mov_b32_e32 v10, v158
	v_cvt_pk_bf16_f32 v52, v10, v10
	s_mov_b32 s13, 0x3e0000
	buffer_store_short v52, v51, s[4:7], s13 offen
	s_waitcnt vmcnt(48)
	v_lshlrev_b32_e32 v159, 16, v159
	v_fmac_f32_e32 v159, s32, v10
	v_mov_b32_e32 v10, v159
	v_add_u32_e32 v53, 0x600000, v47
	global_load_ushort v144, v53, s[58:59] nt
	v_add_u32_e32 v53, 0x620000, v47
	global_load_ushort v145, v53, s[58:59] nt
	v_add_u32_e32 v53, 0x640000, v47
	global_load_ushort v146, v53, s[58:59] nt
	v_add_u32_e32 v53, 0x660000, v47
	global_load_ushort v147, v53, s[58:59] nt
	v_add_u32_e32 v53, 0x680000, v47
	global_load_ushort v148, v53, s[58:59] nt
	v_add_u32_e32 v53, 0x6a0000, v47
	global_load_ushort v149, v53, s[58:59] nt
	v_add_u32_e32 v53, 0x6c0000, v47
	global_load_ushort v150, v53, s[58:59] nt
	v_add_u32_e32 v53, 0x6e0000, v47
	global_load_ushort v151, v53, s[58:59] nt
	v_add_u32_e32 v53, 0x700000, v47
	global_load_ushort v152, v53, s[58:59] nt
	v_add_u32_e32 v53, 0x720000, v47
	global_load_ushort v153, v53, s[58:59] nt
	v_add_u32_e32 v53, 0x740000, v47
	global_load_ushort v154, v53, s[58:59] nt
	v_add_u32_e32 v53, 0x760000, v47
	global_load_ushort v155, v53, s[58:59] nt
	v_add_u32_e32 v53, 0x780000, v47
	global_load_ushort v156, v53, s[58:59] nt
	v_add_u32_e32 v53, 0x7a0000, v47
	global_load_ushort v157, v53, s[58:59] nt
	v_add_u32_e32 v53, 0x7c0000, v47
	global_load_ushort v158, v53, s[58:59] nt
	v_add_u32_e32 v53, 0x7e0000, v47
	global_load_ushort v159, v53, s[58:59] nt
	s_waitcnt lgkmcnt(0)
	s_load_dword s21, s[46:47], 0x600
	s_load_dword s22, s[46:47], 0x620
	s_load_dword s23, s[46:47], 0x640
	s_load_dword s24, s[46:47], 0x660
	s_load_dword s25, s[46:47], 0x680
	s_load_dword s26, s[46:47], 0x6a0
	s_load_dword s27, s[46:47], 0x6c0
	s_load_dword s37, s[46:47], 0x6e0
	s_load_dword s38, s[46:47], 0x700
	s_load_dword s39, s[46:47], 0x720
	s_load_dword s40, s[46:47], 0x740
	s_load_dword s41, s[46:47], 0x760
	s_load_dword s45, s[46:47], 0x780
	s_load_dword s48, s[46:47], 0x7a0
	s_load_dword s49, s[46:47], 0x7c0
	s_load_dword s32, s[46:47], 0x7e0
	v_cvt_pk_bf16_f32 v52, v10, v10
	s_mov_b32 s13, 0x400000
	buffer_store_short v52, v51, s[4:7], s13 offen
	s_waitcnt vmcnt(48)
	v_lshlrev_b32_e32 v128, 16, v128
	v_fmac_f32_e32 v128, s64, v10
	v_mov_b32_e32 v10, v128
	v_cvt_pk_bf16_f32 v52, v10, v10
	s_mov_b32 s13, 0x420000
	buffer_store_short v52, v51, s[4:7], s13 offen
	s_waitcnt vmcnt(48)
	v_lshlrev_b32_e32 v129, 16, v129
	v_fmac_f32_e32 v129, s65, v10
	v_mov_b32_e32 v10, v129
	v_cvt_pk_bf16_f32 v52, v10, v10
	s_mov_b32 s13, 0x440000
	buffer_store_short v52, v51, s[4:7], s13 offen
	s_waitcnt vmcnt(48)
	v_lshlrev_b32_e32 v130, 16, v130
	v_fmac_f32_e32 v130, s66, v10
	v_mov_b32_e32 v10, v130
	v_cvt_pk_bf16_f32 v52, v10, v10
	s_mov_b32 s13, 0x460000
	buffer_store_short v52, v51, s[4:7], s13 offen
	s_waitcnt vmcnt(48)
	v_lshlrev_b32_e32 v131, 16, v131
	v_fmac_f32_e32 v131, s67, v10
	v_mov_b32_e32 v10, v131
	v_cvt_pk_bf16_f32 v52, v10, v10
	s_mov_b32 s13, 0x480000
	buffer_store_short v52, v51, s[4:7], s13 offen
	s_waitcnt vmcnt(48)
	v_lshlrev_b32_e32 v132, 16, v132
	v_fmac_f32_e32 v132, s68, v10
	v_mov_b32_e32 v10, v132
	v_cvt_pk_bf16_f32 v52, v10, v10
	s_mov_b32 s13, 0x4a0000
	buffer_store_short v52, v51, s[4:7], s13 offen
	s_waitcnt vmcnt(48)
	v_lshlrev_b32_e32 v133, 16, v133
	v_fmac_f32_e32 v133, s69, v10
	v_mov_b32_e32 v10, v133
	v_cvt_pk_bf16_f32 v52, v10, v10
	s_mov_b32 s13, 0x4c0000
	buffer_store_short v52, v51, s[4:7], s13 offen
	s_waitcnt vmcnt(48)
	v_lshlrev_b32_e32 v134, 16, v134
	v_fmac_f32_e32 v134, s70, v10
	v_mov_b32_e32 v10, v134
	v_cvt_pk_bf16_f32 v52, v10, v10
	s_mov_b32 s13, 0x4e0000
	buffer_store_short v52, v51, s[4:7], s13 offen
	s_waitcnt vmcnt(48)
	v_lshlrev_b32_e32 v135, 16, v135
	v_fmac_f32_e32 v135, s71, v10
	v_mov_b32_e32 v10, v135
	v_cvt_pk_bf16_f32 v52, v10, v10
	s_mov_b32 s13, 0x500000
	buffer_store_short v52, v51, s[4:7], s13 offen
	s_waitcnt vmcnt(48)
; __device__ __forceinline__ float bf2f(bf16 v) { return __uint_as_float(((unsigned)v) << 16); }
; __device__ __forceinline__ unsigned f2bfu(float f) { return (unsigned)__builtin_bit_cast(unsigned short, (__bf16)f); }
; __global__ void __launch_bounds__(NTHR, 2) k_main(Args a) {
;     ...
;         for (int idx = gtid; idx < 2 * 8 * 8192; idx += gthreads) {
;             const int pn = idx & 8191, h = (idx >> 13) & 7, b = idx >> 16;
;             float run = 0.f;
; #pragma unroll 1
;             for (int c0 = 0; c0 < 64; c0 += 8) {
;                 float st[8], dc[8];
; #pragma unroll
;                 for (int j = 0; j < 8; ++j) { const int bch = (b * 64 + c0 + j) * 8 + h; st[j] = bf2f(__builtin_nontemporal_load(&STATES[(size_t)bch * 8192 + pn])); dc[j] = CDEC[bch]; }
; #pragma unroll
;                 for (int j = 0; j < 8; ++j) { const int bch = (b * 64 + c0 + j) * 8 + h; __builtin_amdgcn_raw_buffer_store_b16((short)f2bfu(run), rsPV, (int)(((unsigned)bch * 8192u + (unsigned)pn) * 2u), 0, 16); run = dc[j] * run + st[j]; }
;             }
;         }
	v_lshlrev_b32_e32 v136, 16, v136
	v_fmac_f32_e32 v136, s72, v10
	v_mov_b32_e32 v10, v136
	v_cvt_pk_bf16_f32 v52, v10, v10
	s_mov_b32 s13, 0x520000
	buffer_store_short v52, v51, s[4:7], s13 offen
	s_waitcnt vmcnt(48)
	v_lshlrev_b32_e32 v137, 16, v137
	v_fmac_f32_e32 v137, s73, v10
	v_mov_b32_e32 v10, v137
	v_cvt_pk_bf16_f32 v52, v10, v10
	s_mov_b32 s13, 0x540000
	buffer_store_short v52, v51, s[4:7], s13 offen
	s_waitcnt vmcnt(48)
	v_lshlrev_b32_e32 v138, 16, v138
	v_fmac_f32_e32 v138, s74, v10
	v_mov_b32_e32 v10, v138
	v_cvt_pk_bf16_f32 v52, v10, v10
	s_mov_b32 s13, 0x560000
	buffer_store_short v52, v51, s[4:7], s13 offen
	s_waitcnt vmcnt(48)
	v_lshlrev_b32_e32 v139, 16, v139
	v_fmac_f32_e32 v139, s75, v10
	v_mov_b32_e32 v10, v139
	v_cvt_pk_bf16_f32 v52, v10, v10
	s_mov_b32 s13, 0x580000
	buffer_store_short v52, v51, s[4:7], s13 offen
	s_waitcnt vmcnt(48)
	v_lshlrev_b32_e32 v140, 16, v140
	v_fmac_f32_e32 v140, s76, v10
	v_mov_b32_e32 v10, v140
	v_cvt_pk_bf16_f32 v52, v10, v10
	s_mov_b32 s13, 0x5a0000
	buffer_store_short v52, v51, s[4:7], s13 offen
	s_waitcnt vmcnt(48)
	v_lshlrev_b32_e32 v141, 16, v141
	v_fmac_f32_e32 v141, s77, v10
	v_mov_b32_e32 v10, v141
	v_cvt_pk_bf16_f32 v52, v10, v10
	s_mov_b32 s13, 0x5c0000
	buffer_store_short v52, v51, s[4:7], s13 offen
	s_waitcnt vmcnt(48)
	v_lshlrev_b32_e32 v142, 16, v142
	v_fmac_f32_e32 v142, s78, v10
	v_mov_b32_e32 v10, v142
	v_cvt_pk_bf16_f32 v52, v10, v10
	s_mov_b32 s13, 0x5e0000
	buffer_store_short v52, v51, s[4:7], s13 offen
	s_waitcnt vmcnt(48)
	v_lshlrev_b32_e32 v143, 16, v143
	v_fmac_f32_e32 v143, s79, v10
	v_mov_b32_e32 v10, v143
	s_waitcnt lgkmcnt(0)
	v_cvt_pk_bf16_f32 v52, v10, v10
	s_mov_b32 s13, 0x600000
	buffer_store_short v52, v51, s[4:7], s13 offen
	s_waitcnt vmcnt(32)
	v_lshlrev_b32_e32 v144, 16, v144
	v_fmac_f32_e32 v144, s21, v10
	v_mov_b32_e32 v10, v144
	v_cvt_pk_bf16_f32 v52, v10, v10
	s_mov_b32 s13, 0x620000
	buffer_store_short v52, v51, s[4:7], s13 offen
	s_waitcnt vmcnt(32)
	v_lshlrev_b32_e32 v145, 16, v145
	v_fmac_f32_e32 v145, s22, v10
	v_mov_b32_e32 v10, v145
	v_cvt_pk_bf16_f32 v52, v10, v10
	s_mov_b32 s13, 0x640000
	buffer_store_short v52, v51, s[4:7], s13 offen
	s_waitcnt vmcnt(32)
	v_lshlrev_b32_e32 v146, 16, v146
	v_fmac_f32_e32 v146, s23, v10
	v_mov_b32_e32 v10, v146
	v_cvt_pk_bf16_f32 v52, v10, v10
	s_mov_b32 s13, 0x660000
	buffer_store_short v52, v51, s[4:7], s13 offen
	s_waitcnt vmcnt(32)
	v_lshlrev_b32_e32 v147, 16, v147
	v_fmac_f32_e32 v147, s24, v10
	v_mov_b32_e32 v10, v147
	v_cvt_pk_bf16_f32 v52, v10, v10
	s_mov_b32 s13, 0x680000
	buffer_store_short v52, v51, s[4:7], s13 offen
	s_waitcnt vmcnt(32)
	v_lshlrev_b32_e32 v148, 16, v148
	v_fmac_f32_e32 v148, s25, v10
	v_mov_b32_e32 v10, v148
	v_cvt_pk_bf16_f32 v52, v10, v10
	s_mov_b32 s13, 0x6a0000
	buffer_store_short v52, v51, s[4:7], s13 offen
	s_waitcnt vmcnt(32)
	v_lshlrev_b32_e32 v149, 16, v149
	v_fmac_f32_e32 v149, s26, v10
	v_mov_b32_e32 v10, v149
	v_cvt_pk_bf16_f32 v52, v10, v10
	s_mov_b32 s13, 0x6c0000
	buffer_store_short v52, v51, s[4:7], s13 offen
	s_waitcnt vmcnt(32)
	v_lshlrev_b32_e32 v150, 16, v150
	v_fmac_f32_e32 v150, s27, v10
	v_mov_b32_e32 v10, v150
	v_cvt_pk_bf16_f32 v52, v10, v10
	s_mov_b32 s13, 0x6e0000
	buffer_store_short v52, v51, s[4:7], s13 offen
	s_waitcnt vmcnt(32)
	v_lshlrev_b32_e32 v151, 16, v151
	v_fmac_f32_e32 v151, s37, v10
	v_mov_b32_e32 v10, v151
	v_cvt_pk_bf16_f32 v52, v10, v10
	s_mov_b32 s13, 0x700000
	buffer_store_short v52, v51, s[4:7], s13 offen
	s_waitcnt vmcnt(32)
	v_lshlrev_b32_e32 v152, 16, v152
	v_fmac_f32_e32 v152, s38, v10
	v_mov_b32_e32 v10, v152
	v_cvt_pk_bf16_f32 v52, v10, v10
	s_mov_b32 s13, 0x720000
	buffer_store_short v52, v51, s[4:7], s13 offen
	s_waitcnt vmcnt(32)
	v_lshlrev_b32_e32 v153, 16, v153
	v_fmac_f32_e32 v153, s39, v10
	v_mov_b32_e32 v10, v153
	v_cvt_pk_bf16_f32 v52, v10, v10
	s_mov_b32 s13, 0x740000
	buffer_store_short v52, v51, s[4:7], s13 offen
	s_waitcnt vmcnt(32)
	v_lshlrev_b32_e32 v154, 16, v154
	v_fmac_f32_e32 v154, s40, v10
	v_mov_b32_e32 v10, v154
	v_cvt_pk_bf16_f32 v52, v10, v10
	s_mov_b32 s13, 0x760000
	buffer_store_short v52, v51, s[4:7], s13 offen
	s_waitcnt vmcnt(32)
	v_lshlrev_b32_e32 v155, 16, v155
	v_fmac_f32_e32 v155, s41, v10
	v_mov_b32_e32 v10, v155
	v_cvt_pk_bf16_f32 v52, v10, v10
	s_mov_b32 s13, 0x780000
	buffer_store_short v52, v51, s[4:7], s13 offen
	s_waitcnt vmcnt(32)
	v_lshlrev_b32_e32 v156, 16, v156
	v_fmac_f32_e32 v156, s45, v10
	v_mov_b32_e32 v10, v156
	v_cvt_pk_bf16_f32 v52, v10, v10
	s_mov_b32 s13, 0x7a0000
	buffer_store_short v52, v51, s[4:7], s13 offen
	s_waitcnt vmcnt(32)
	v_lshlrev_b32_e32 v157, 16, v157
	v_fmac_f32_e32 v157, s48, v10
	v_mov_b32_e32 v10, v157
	v_cvt_pk_bf16_f32 v52, v10, v10
	s_mov_b32 s13, 0x7c0000
	buffer_store_short v52, v51, s[4:7], s13 offen
	s_waitcnt vmcnt(32)
	v_lshlrev_b32_e32 v158, 16, v158
	v_fmac_f32_e32 v158, s49, v10
	v_mov_b32_e32 v10, v158
	v_cvt_pk_bf16_f32 v52, v10, v10
	s_mov_b32 s13, 0x7e0000
	buffer_store_short v52, v51, s[4:7], s13 offen
	s_waitcnt vmcnt(32)
	v_lshlrev_b32_e32 v159, 16, v159
	v_fmac_f32_e32 v159, s32, v10
	v_mov_b32_e32 v10, v159
	v_add_u32_e32 v8, s56, v8
	v_cmp_lt_i32_e32 vcc, s11, v8
	s_or_b64 s[8:9], vcc, s[8:9]
	v_add_u32_e32 v9, s3, v9
	s_andn2_b64 exec, exec, s[8:9]
	s_cbranch_execnz .LBB0_377
